# v61 with helper B reduced to 7168 tiles (14 per wave) so it fits the P8 idle window
# speedup vs baseline: 1.0026x; 1.0026x over previous
; #define LAS __attribute__((address_space(3)))
; __device__ __forceinline__ unsigned pk2(float lo, float hi) { return pg8::cvt_pk_bf16(lo, hi); }
; __device__ __forceinline__ void p0_load(const float* W, int N, int k0, int n0, int lane, f32x4 (&v)[16]) {
;     const int c = lane & 15, rq = lane >> 4;
;     int col = n0 + 4 * c; col = col < N - 4 ? col : N - 4;
;     const float* p = W + (size_t)(k0 + rq) * N + col;
; #pragma unroll
;     for (int j = 0; j < 16; ++j) v[j] = __builtin_nontemporal_load((const f32x4*)(p + (size_t)(4 * j) * N));
; }
; __device__ __forceinline__ void p0_finish(bf16* WT, const float* gain, int N, int k0, int n0, int ldw, int blk, int off, int lane, const f32x4 (&v)[16], LAS float* scr) {
;     const int c = lane & 15, rq = lane >> 4, c8 = lane & 7;
;     f32x4 g0 = {1.f, 1.f, 1.f, 1.f}, g1 = g0;
;     if (gain) { g0 = *(const f32x4*)(gain + k0 + 8 * c8); g1 = *(const f32x4*)(gain + k0 + 8 * c8 + 4); }
; #pragma unroll
;     for (int j = 0; j < 16; ++j) { LAS float* s = scr + (4 * j + rq) * 65 + 4 * c; s[0] = v[j][0]; s[1] = v[j][1]; s[2] = v[j][2]; s[3] = v[j][3]; }
;     asm volatile("s_waitcnt lgkmcnt(0)" ::: "memory");
; #pragma unroll
;     for (int jj = 0; jj < 8; ++jj) { const int n = (lane >> 3) + 8 * jj; const LAS float* s = scr + (8 * c8) * 65 + n;
;         u32x4 o; o.x = pk2(s[0 * 65] * g0[0], s[1 * 65] * g0[1]); o.y = pk2(s[2 * 65] * g0[2], s[3 * 65] * g0[3]); o.z = pk2(s[4 * 65] * g1[0], s[5 * 65] * g1[1]); o.w = pk2(s[6 * 65] * g1[2], s[7 * 65] * g1[3]);
;         const int ng = n0 + n;
;         if (ng < N) { const int row = (ng >> 7) * blk + (ng & 127) + off; __builtin_nontemporal_store(o, (u32x4*)(WT + (size_t)row * ldw + k0 + 8 * c8)); } }
;     asm volatile("s_waitcnt lgkmcnt(0)" ::: "memory");
; }
.LBB0_1140:
	s_cmpk_lt_u32 s8, 0xc0
	s_cbranch_scc1 .Lhn_done
	v_writelane_b32 v238, s0, 0
	v_writelane_b32 v238, s1, 1
	v_writelane_b32 v238, s2, 2
	v_writelane_b32 v238, s3, 3
	v_writelane_b32 v238, s4, 4
	v_writelane_b32 v238, s5, 5
	v_writelane_b32 v238, s6, 6
	v_writelane_b32 v238, s7, 7
	v_writelane_b32 v238, s8, 8
	v_writelane_b32 v238, s9, 9
	v_writelane_b32 v238, s10, 10
	v_writelane_b32 v238, s11, 11
	v_writelane_b32 v238, s12, 12
	v_writelane_b32 v238, s13, 13
	v_writelane_b32 v238, s14, 14
	v_writelane_b32 v238, s15, 15
	v_writelane_b32 v238, s16, 16
	v_writelane_b32 v238, s17, 17
	v_writelane_b32 v238, s18, 18
	v_writelane_b32 v238, s19, 19
	v_writelane_b32 v238, s20, 20
	v_writelane_b32 v238, s21, 21
	v_writelane_b32 v238, s22, 22
	v_writelane_b32 v238, s23, 23
	v_writelane_b32 v238, s24, 24
	v_writelane_b32 v238, s25, 25
	v_writelane_b32 v238, s26, 26
	v_writelane_b32 v238, s27, 27
	v_writelane_b32 v238, s28, 28
	v_writelane_b32 v238, s29, 29
	v_writelane_b32 v238, s30, 30
	v_writelane_b32 v238, s31, 31
	v_writelane_b32 v238, s32, 32
	v_writelane_b32 v238, s33, 33
	v_writelane_b32 v238, s34, 34
	v_writelane_b32 v238, s35, 35
	v_writelane_b32 v238, s36, 36
	v_writelane_b32 v238, s37, 37
	v_writelane_b32 v238, s38, 38
	v_writelane_b32 v238, s39, 39
	v_writelane_b32 v238, s40, 40
	v_writelane_b32 v238, s41, 41
	v_writelane_b32 v238, s42, 42
	v_writelane_b32 v238, s43, 43
	v_writelane_b32 v238, s44, 44
	v_writelane_b32 v238, s45, 45
	v_writelane_b32 v238, s46, 46
	v_writelane_b32 v238, s47, 47
	v_writelane_b32 v238, s48, 48
	v_writelane_b32 v238, s49, 49
	v_writelane_b32 v238, s50, 50
	v_writelane_b32 v238, s51, 51
	v_writelane_b32 v238, s52, 52
	v_writelane_b32 v238, s53, 53
	v_writelane_b32 v238, s54, 54
	v_writelane_b32 v238, s55, 55
	v_writelane_b32 v238, s56, 56
	v_writelane_b32 v238, s57, 57
	v_writelane_b32 v238, s58, 58
	v_writelane_b32 v238, s59, 59
	v_writelane_b32 v238, s60, 60
	v_writelane_b32 v238, s61, 61
	v_writelane_b32 v238, s62, 62
	v_writelane_b32 v238, s63, 63
	v_writelane_b32 v239, s64, 0
	v_writelane_b32 v239, s65, 1
	v_writelane_b32 v239, s66, 2
	v_writelane_b32 v239, s67, 3
	v_writelane_b32 v239, s68, 4
	v_writelane_b32 v239, s69, 5
	v_writelane_b32 v239, s70, 6
	v_writelane_b32 v239, s71, 7
	v_writelane_b32 v239, s72, 8
	v_writelane_b32 v239, s73, 9
	v_writelane_b32 v239, s74, 10
	v_writelane_b32 v239, s75, 11
	v_writelane_b32 v239, s76, 12
	v_writelane_b32 v239, s77, 13
	v_writelane_b32 v239, s78, 14
	v_writelane_b32 v239, s79, 15
	v_writelane_b32 v239, s80, 16
	v_writelane_b32 v239, s81, 17
	v_writelane_b32 v239, s82, 18
	v_writelane_b32 v239, s83, 19
	v_writelane_b32 v239, s84, 20
	v_writelane_b32 v239, s85, 21
	v_writelane_b32 v239, s86, 22
	v_writelane_b32 v239, s87, 23
	v_writelane_b32 v239, s88, 24
	v_writelane_b32 v239, s89, 25
	v_writelane_b32 v239, s90, 26
	v_writelane_b32 v239, s91, 27
	v_writelane_b32 v239, s92, 28
	v_writelane_b32 v239, s93, 29
	v_writelane_b32 v239, s94, 30
	v_writelane_b32 v239, s95, 31
	v_writelane_b32 v239, s96, 32
	v_writelane_b32 v239, s97, 33
	v_writelane_b32 v239, s98, 34
	v_writelane_b32 v239, s99, 35
	v_writelane_b32 v239, s100, 36
	v_writelane_b32 v239, s101, 37
	v_writelane_b32 v239, vcc_lo, 38
	v_writelane_b32 v239, vcc_hi, 39
	v_writelane_b32 v239, m0, 40
	s_add_i32 s16, s8, 0xffffff40
	s_lshl_b32 s16, s16, 3
	s_add_i32 s16, s16, s28
	s_load_dwordx2 s[30:31], s[0:1], 0x78
	v_mbcnt_lo_u32_b32 v146, -1, 0
	v_mbcnt_hi_u32_b32 v146, -1, v146
	s_and_b32 s17, s16, 63
	s_lshr_b32 s18, s16, 6
	s_add_i32 s18, s18, 60
	s_mul_i32 s19, s28, 0x4100
	v_lshrrev_b32_e32 v131, 4, v146
	v_and_b32_e32 v133, 15, v146
	v_mul_u32_u24_e32 v128, 0x104, v131
	v_lshl_add_u32 v128, v133, 4, v128
	v_add_u32_e32 v128, s19, v128
	v_lshlrev_b32_e32 v131, 14, v131
	v_lshl_add_u32 v131, v133, 4, v131
	v_and_b32_e32 v133, 7, v146
	v_lshrrev_b32_e32 v132, 3, v146
	v_mul_u32_u24_e32 v129, 0x820, v133
	v_lshl_add_u32 v129, v132, 2, v129
	v_add_u32_e32 v129, s19, v129
	v_add_u32_e32 v130, 0x400, v129
	v_mul_u32_u24_e32 v132, 0x5680, v132
	v_lshl_add_u32 v132, v133, 4, v132
	s_waitcnt lgkmcnt(0)
; __device__ __forceinline__ void p0_load(const float* W, int N, int k0, int n0, int lane, f32x4 (&v)[16]) {
;     const int c = lane & 15, rq = lane >> 4;
;     int col = n0 + 4 * c; col = col < N - 4 ? col : N - 4;
;     const float* p = W + (size_t)(k0 + rq) * N + col;
; #pragma unroll
;     for (int j = 0; j < 16; ++j) v[j] = __builtin_nontemporal_load((const f32x4*)(p + (size_t)(4 * j) * N));
	s_lshl_b32 s2, s17, 8
	s_add_u32 s20, s30, s2
	s_addc_u32 s21, s31, 0
	s_lshr_b32 s3, s18, 12
	s_lshl_b32 s2, s18, 20
	s_add_u32 s20, s20, s2
	s_addc_u32 s21, s21, s3
	s_add_u32 s22, s14, 0x25000000
	s_addc_u32 s23, s15, 0
	s_mul_i32 s2, s17, 0x15a000
	s_add_u32 s22, s22, s2
	s_addc_u32 s23, s23, 0
	s_lshl_b32 s2, s18, 7
	s_add_u32 s22, s22, s2
	s_addc_u32 s23, s23, 0
	s_mov_b32 s26, 0
	s_mov_b32 s27, 1
	global_load_dwordx4 v[0:3], v131, s[20:21] nt
	s_add_u32 s24, s20, 0x10000
	s_addc_u32 s25, s21, 0
	global_load_dwordx4 v[4:7], v131, s[24:25] nt
	s_add_u32 s24, s20, 0x20000
	s_addc_u32 s25, s21, 0
	global_load_dwordx4 v[8:11], v131, s[24:25] nt
	s_add_u32 s24, s20, 0x30000
	s_addc_u32 s25, s21, 0
	global_load_dwordx4 v[12:15], v131, s[24:25] nt
	s_add_u32 s24, s20, 0x40000
	s_addc_u32 s25, s21, 0
	global_load_dwordx4 v[16:19], v131, s[24:25] nt
	s_add_u32 s24, s20, 0x50000
	s_addc_u32 s25, s21, 0
	global_load_dwordx4 v[20:23], v131, s[24:25] nt
	s_add_u32 s24, s20, 0x60000
	s_addc_u32 s25, s21, 0
	global_load_dwordx4 v[24:27], v131, s[24:25] nt
	s_add_u32 s24, s20, 0x70000
	s_addc_u32 s25, s21, 0
	global_load_dwordx4 v[28:31], v131, s[24:25] nt
	s_add_u32 s24, s20, 0x80000
	s_addc_u32 s25, s21, 0
	global_load_dwordx4 v[32:35], v131, s[24:25] nt
	s_add_u32 s24, s20, 0x90000
	s_addc_u32 s25, s21, 0
	global_load_dwordx4 v[36:39], v131, s[24:25] nt
	s_add_u32 s24, s20, 0xa0000
	s_addc_u32 s25, s21, 0
	global_load_dwordx4 v[40:43], v131, s[24:25] nt
	s_add_u32 s24, s20, 0xb0000
	s_addc_u32 s25, s21, 0
	global_load_dwordx4 v[44:47], v131, s[24:25] nt
	s_add_u32 s24, s20, 0xc0000
	s_addc_u32 s25, s21, 0
	global_load_dwordx4 v[48:51], v131, s[24:25] nt
	s_add_u32 s24, s20, 0xd0000
	s_addc_u32 s25, s21, 0
	global_load_dwordx4 v[52:55], v131, s[24:25] nt
	s_add_u32 s24, s20, 0xe0000
	s_addc_u32 s25, s21, 0
	global_load_dwordx4 v[56:59], v131, s[24:25] nt
	s_add_u32 s24, s20, 0xf0000
	s_addc_u32 s25, s21, 0
	global_load_dwordx4 v[60:63], v131, s[24:25] nt
	s_cmp_lt_u32 s27, 14
	s_cselect_b32 s2, 0x800000, 0
	s_add_u32 s20, s20, s2
	s_addc_u32 s21, s21, 0
	s_add_i32 s27, s27, 1
	global_load_dwordx4 v[64:67], v131, s[20:21] nt
	s_add_u32 s24, s20, 0x10000
	s_addc_u32 s25, s21, 0
	global_load_dwordx4 v[68:71], v131, s[24:25] nt
	s_add_u32 s24, s20, 0x20000
	s_addc_u32 s25, s21, 0
	global_load_dwordx4 v[72:75], v131, s[24:25] nt
	s_add_u32 s24, s20, 0x30000
	s_addc_u32 s25, s21, 0
	global_load_dwordx4 v[76:79], v131, s[24:25] nt
	s_add_u32 s24, s20, 0x40000
	s_addc_u32 s25, s21, 0
	global_load_dwordx4 v[80:83], v131, s[24:25] nt
	s_add_u32 s24, s20, 0x50000
	s_addc_u32 s25, s21, 0
	global_load_dwordx4 v[84:87], v131, s[24:25] nt
	s_add_u32 s24, s20, 0x60000
	s_addc_u32 s25, s21, 0
	global_load_dwordx4 v[88:91], v131, s[24:25] nt
	s_add_u32 s24, s20, 0x70000
	s_addc_u32 s25, s21, 0
	global_load_dwordx4 v[92:95], v131, s[24:25] nt
	s_add_u32 s24, s20, 0x80000
	s_addc_u32 s25, s21, 0
	global_load_dwordx4 v[96:99], v131, s[24:25] nt
	s_add_u32 s24, s20, 0x90000
	s_addc_u32 s25, s21, 0
	global_load_dwordx4 v[100:103], v131, s[24:25] nt
	s_add_u32 s24, s20, 0xa0000
	s_addc_u32 s25, s21, 0
	global_load_dwordx4 v[104:107], v131, s[24:25] nt
	s_add_u32 s24, s20, 0xb0000
	s_addc_u32 s25, s21, 0
	global_load_dwordx4 v[108:111], v131, s[24:25] nt
	s_add_u32 s24, s20, 0xc0000
	s_addc_u32 s25, s21, 0
	global_load_dwordx4 v[112:115], v131, s[24:25] nt
	s_add_u32 s24, s20, 0xd0000
	s_addc_u32 s25, s21, 0
	global_load_dwordx4 v[116:119], v131, s[24:25] nt
	s_add_u32 s24, s20, 0xe0000
	s_addc_u32 s25, s21, 0
	global_load_dwordx4 v[120:123], v131, s[24:25] nt
	s_add_u32 s24, s20, 0xf0000
	s_addc_u32 s25, s21, 0
	global_load_dwordx4 v[124:127], v131, s[24:25] nt

; #define LAS __attribute__((address_space(3)))
; __device__ __forceinline__ unsigned pk2(float lo, float hi) { return pg8::cvt_pk_bf16(lo, hi); }
; __device__ __forceinline__ void p0_finish(bf16* WT, const float* gain, int N, int k0, int n0, int ldw, int blk, int off, int lane, const f32x4 (&v)[16], LAS float* scr) {
;     const int c = lane & 15, rq = lane >> 4, c8 = lane & 7;
;     f32x4 g0 = {1.f, 1.f, 1.f, 1.f}, g1 = g0;
;     if (gain) { g0 = *(const f32x4*)(gain + k0 + 8 * c8); g1 = *(const f32x4*)(gain + k0 + 8 * c8 + 4); }
; #pragma unroll
;     for (int j = 0; j < 16; ++j) { LAS float* s = scr + (4 * j + rq) * 65 + 4 * c; s[0] = v[j][0]; s[1] = v[j][1]; s[2] = v[j][2]; s[3] = v[j][3]; }
;     asm volatile("s_waitcnt lgkmcnt(0)" ::: "memory");
; #pragma unroll
;     for (int jj = 0; jj < 8; ++jj) { const int n = (lane >> 3) + 8 * jj; const LAS float* s = scr + (8 * c8) * 65 + n;
;         u32x4 o; o.x = pk2(s[0 * 65] * g0[0], s[1 * 65] * g0[1]); o.y = pk2(s[2 * 65] * g0[2], s[3 * 65] * g0[3]); o.z = pk2(s[4 * 65] * g1[0], s[5 * 65] * g1[1]); o.w = pk2(s[6 * 65] * g1[2], s[7 * 65] * g1[3]);
;         const int ng = n0 + n;
;         if (ng < N) { const int row = (ng >> 7) * blk + (ng & 127) + off; __builtin_nontemporal_store(o, (u32x4*)(WT + (size_t)row * ldw + k0 + 8 * c8)); } }
;     asm volatile("s_waitcnt lgkmcnt(0)" ::: "memory");
; }
.Lhn_w0:
	s_waitcnt vmcnt(32)
	ds_write2_b32 v128, v0, v1 offset1:1
	ds_write2_b32 v128, v2, v3 offset0:2 offset1:3
	v_add_u32_e32 v133, 0x410, v128
	ds_write2_b32 v133, v4, v5 offset1:1
	ds_write2_b32 v133, v6, v7 offset0:2 offset1:3
	v_add_u32_e32 v147, 0x820, v128
	ds_write2_b32 v147, v8, v9 offset1:1
	ds_write2_b32 v147, v10, v11 offset0:2 offset1:3
	v_add_u32_e32 v133, 0xc30, v128
	ds_write2_b32 v133, v12, v13 offset1:1
	ds_write2_b32 v133, v14, v15 offset0:2 offset1:3
	v_add_u32_e32 v147, 0x1040, v128
	ds_write2_b32 v147, v16, v17 offset1:1
	ds_write2_b32 v147, v18, v19 offset0:2 offset1:3
	v_add_u32_e32 v133, 0x1450, v128
	ds_write2_b32 v133, v20, v21 offset1:1
	ds_write2_b32 v133, v22, v23 offset0:2 offset1:3
	v_add_u32_e32 v147, 0x1860, v128
	ds_write2_b32 v147, v24, v25 offset1:1
	ds_write2_b32 v147, v26, v27 offset0:2 offset1:3
	v_add_u32_e32 v133, 0x1c70, v128
	ds_write2_b32 v133, v28, v29 offset1:1
	ds_write2_b32 v133, v30, v31 offset0:2 offset1:3
	v_add_u32_e32 v147, 0x2080, v128
	ds_write2_b32 v147, v32, v33 offset1:1
	ds_write2_b32 v147, v34, v35 offset0:2 offset1:3
	v_add_u32_e32 v133, 0x2490, v128
	ds_write2_b32 v133, v36, v37 offset1:1
	ds_write2_b32 v133, v38, v39 offset0:2 offset1:3
	v_add_u32_e32 v147, 0x28a0, v128
	ds_write2_b32 v147, v40, v41 offset1:1
	ds_write2_b32 v147, v42, v43 offset0:2 offset1:3
	v_add_u32_e32 v133, 0x2cb0, v128
	ds_write2_b32 v133, v44, v45 offset1:1
	ds_write2_b32 v133, v46, v47 offset0:2 offset1:3
	v_add_u32_e32 v147, 0x30c0, v128
	ds_write2_b32 v147, v48, v49 offset1:1
	ds_write2_b32 v147, v50, v51 offset0:2 offset1:3
	v_add_u32_e32 v133, 0x34d0, v128
	ds_write2_b32 v133, v52, v53 offset1:1
	ds_write2_b32 v133, v54, v55 offset0:2 offset1:3
	v_add_u32_e32 v147, 0x38e0, v128
	ds_write2_b32 v147, v56, v57 offset1:1
	ds_write2_b32 v147, v58, v59 offset0:2 offset1:3
	v_add_u32_e32 v133, 0x3cf0, v128
	ds_write2_b32 v133, v60, v61 offset1:1
	ds_write2_b32 v133, v62, v63 offset0:2 offset1:3
	s_waitcnt lgkmcnt(0)
	s_cmp_lt_u32 s27, 14
	s_cselect_b32 s2, 0x800000, 0
	s_add_u32 s20, s20, s2
	s_addc_u32 s21, s21, 0
	s_add_i32 s27, s27, 1
	global_load_dwordx4 v[0:3], v131, s[20:21] nt
	s_add_u32 s24, s20, 0x10000
	s_addc_u32 s25, s21, 0
	global_load_dwordx4 v[4:7], v131, s[24:25] nt
	s_add_u32 s24, s20, 0x20000
	s_addc_u32 s25, s21, 0
	global_load_dwordx4 v[8:11], v131, s[24:25] nt
	s_add_u32 s24, s20, 0x30000
	s_addc_u32 s25, s21, 0
	global_load_dwordx4 v[12:15], v131, s[24:25] nt
	s_add_u32 s24, s20, 0x40000
	s_addc_u32 s25, s21, 0
	global_load_dwordx4 v[16:19], v131, s[24:25] nt
	s_add_u32 s24, s20, 0x50000
	s_addc_u32 s25, s21, 0
	global_load_dwordx4 v[20:23], v131, s[24:25] nt
	s_add_u32 s24, s20, 0x60000
	s_addc_u32 s25, s21, 0
	global_load_dwordx4 v[24:27], v131, s[24:25] nt
	s_add_u32 s24, s20, 0x70000
	s_addc_u32 s25, s21, 0
	global_load_dwordx4 v[28:31], v131, s[24:25] nt
	s_add_u32 s24, s20, 0x80000
	s_addc_u32 s25, s21, 0
	global_load_dwordx4 v[32:35], v131, s[24:25] nt
	s_add_u32 s24, s20, 0x90000
	s_addc_u32 s25, s21, 0
	global_load_dwordx4 v[36:39], v131, s[24:25] nt
	s_add_u32 s24, s20, 0xa0000
	s_addc_u32 s25, s21, 0
	global_load_dwordx4 v[40:43], v131, s[24:25] nt
	s_add_u32 s24, s20, 0xb0000
	s_addc_u32 s25, s21, 0
	global_load_dwordx4 v[44:47], v131, s[24:25] nt
	s_add_u32 s24, s20, 0xc0000
	s_addc_u32 s25, s21, 0
	global_load_dwordx4 v[48:51], v131, s[24:25] nt
	s_add_u32 s24, s20, 0xd0000
	s_addc_u32 s25, s21, 0
	global_load_dwordx4 v[52:55], v131, s[24:25] nt
	s_add_u32 s24, s20, 0xe0000
	s_addc_u32 s25, s21, 0
	global_load_dwordx4 v[56:59], v131, s[24:25] nt
	s_add_u32 s24, s20, 0xf0000
	s_addc_u32 s25, s21, 0
	global_load_dwordx4 v[60:63], v131, s[24:25] nt
	ds_read2_b32 v[134:135], v129 offset0:0 offset1:65
	ds_read2_b32 v[136:137], v129 offset0:130 offset1:195
	ds_read2_b32 v[138:139], v130 offset0:4 offset1:69
	ds_read2_b32 v[140:141], v130 offset0:134 offset1:199
	ds_read2_b32 v[148:149], v129 offset0:8 offset1:73
	ds_read2_b32 v[150:151], v129 offset0:138 offset1:203
	ds_read2_b32 v[152:153], v130 offset0:12 offset1:77
	ds_read2_b32 v[154:155], v130 offset0:142 offset1:207
	s_mov_b64 s[24:25], s[22:23]
	s_waitcnt lgkmcnt(4)
	v_cvt_pk_bf16_f32 v142, v134, v135
	v_cvt_pk_bf16_f32 v143, v136, v137
	v_cvt_pk_bf16_f32 v144, v138, v139
	v_cvt_pk_bf16_f32 v145, v140, v141
	global_store_dwordx4 v132, v[142:145], s[24:25] nt
	ds_read2_b32 v[134:135], v129 offset0:16 offset1:81
	ds_read2_b32 v[136:137], v129 offset0:146 offset1:211
	ds_read2_b32 v[138:139], v130 offset0:20 offset1:85
	ds_read2_b32 v[140:141], v130 offset0:150 offset1:215
	s_add_u32 s24, s22, 0x2b400
	s_addc_u32 s25, s23, 0
	s_waitcnt lgkmcnt(4)
	v_cvt_pk_bf16_f32 v156, v148, v149
	v_cvt_pk_bf16_f32 v157, v150, v151
	v_cvt_pk_bf16_f32 v158, v152, v153
	v_cvt_pk_bf16_f32 v159, v154, v155
	global_store_dwordx4 v132, v[156:159], s[24:25] nt
	ds_read2_b32 v[148:149], v129 offset0:24 offset1:89
	ds_read2_b32 v[150:151], v129 offset0:154 offset1:219
	ds_read2_b32 v[152:153], v130 offset0:28 offset1:93
	ds_read2_b32 v[154:155], v130 offset0:158 offset1:223
	s_add_u32 s24, s22, 0x56800
	s_addc_u32 s25, s23, 0
	s_waitcnt lgkmcnt(4)
	v_cvt_pk_bf16_f32 v142, v134, v135
	v_cvt_pk_bf16_f32 v143, v136, v137
	v_cvt_pk_bf16_f32 v144, v138, v139
	v_cvt_pk_bf16_f32 v145, v140, v141
	global_store_dwordx4 v132, v[142:145], s[24:25] nt
	ds_read2_b32 v[134:135], v129 offset0:32 offset1:97
	ds_read2_b32 v[136:137], v129 offset0:162 offset1:227
	ds_read2_b32 v[138:139], v130 offset0:36 offset1:101
	ds_read2_b32 v[140:141], v130 offset0:166 offset1:231
	s_add_u32 s24, s22, 0x81c00
	s_addc_u32 s25, s23, 0
	s_waitcnt lgkmcnt(4)
; #define LAS __attribute__((address_space(3)))
; __device__ __forceinline__ unsigned pk2(float lo, float hi) { return pg8::cvt_pk_bf16(lo, hi); }
; __device__ __forceinline__ void p0_finish(bf16* WT, const float* gain, int N, int k0, int n0, int ldw, int blk, int off, int lane, const f32x4 (&v)[16], LAS float* scr) {
;     const int c = lane & 15, rq = lane >> 4, c8 = lane & 7;
;     f32x4 g0 = {1.f, 1.f, 1.f, 1.f}, g1 = g0;
;     if (gain) { g0 = *(const f32x4*)(gain + k0 + 8 * c8); g1 = *(const f32x4*)(gain + k0 + 8 * c8 + 4); }
; #pragma unroll
;     for (int j = 0; j < 16; ++j) { LAS float* s = scr + (4 * j + rq) * 65 + 4 * c; s[0] = v[j][0]; s[1] = v[j][1]; s[2] = v[j][2]; s[3] = v[j][3]; }
;     asm volatile("s_waitcnt lgkmcnt(0)" ::: "memory");
; #pragma unroll
;     for (int jj = 0; jj < 8; ++jj) { const int n = (lane >> 3) + 8 * jj; const LAS float* s = scr + (8 * c8) * 65 + n;
;         u32x4 o; o.x = pk2(s[0 * 65] * g0[0], s[1 * 65] * g0[1]); o.y = pk2(s[2 * 65] * g0[2], s[3 * 65] * g0[3]); o.z = pk2(s[4 * 65] * g1[0], s[5 * 65] * g1[1]); o.w = pk2(s[6 * 65] * g1[2], s[7 * 65] * g1[3]);
;         const int ng = n0 + n;
;         if (ng < N) { const int row = (ng >> 7) * blk + (ng & 127) + off; __builtin_nontemporal_store(o, (u32x4*)(WT + (size_t)row * ldw + k0 + 8 * c8)); } }
;     asm volatile("s_waitcnt lgkmcnt(0)" ::: "memory");
; }
	v_cvt_pk_bf16_f32 v156, v148, v149
	v_cvt_pk_bf16_f32 v157, v150, v151
	v_cvt_pk_bf16_f32 v158, v152, v153
	v_cvt_pk_bf16_f32 v159, v154, v155
	global_store_dwordx4 v132, v[156:159], s[24:25] nt
	ds_read2_b32 v[148:149], v129 offset0:40 offset1:105
	ds_read2_b32 v[150:151], v129 offset0:170 offset1:235
	ds_read2_b32 v[152:153], v130 offset0:44 offset1:109
	ds_read2_b32 v[154:155], v130 offset0:174 offset1:239
	s_add_u32 s24, s22, 0xad000
	s_addc_u32 s25, s23, 0
	s_waitcnt lgkmcnt(4)
	v_cvt_pk_bf16_f32 v142, v134, v135
	v_cvt_pk_bf16_f32 v143, v136, v137
	v_cvt_pk_bf16_f32 v144, v138, v139
	v_cvt_pk_bf16_f32 v145, v140, v141
	global_store_dwordx4 v132, v[142:145], s[24:25] nt
	ds_read2_b32 v[134:135], v129 offset0:48 offset1:113
	ds_read2_b32 v[136:137], v129 offset0:178 offset1:243
	ds_read2_b32 v[138:139], v130 offset0:52 offset1:117
	ds_read2_b32 v[140:141], v130 offset0:182 offset1:247
	s_add_u32 s24, s22, 0xd8400
	s_addc_u32 s25, s23, 0
	s_waitcnt lgkmcnt(4)
	v_cvt_pk_bf16_f32 v156, v148, v149
	v_cvt_pk_bf16_f32 v157, v150, v151
	v_cvt_pk_bf16_f32 v158, v152, v153
	v_cvt_pk_bf16_f32 v159, v154, v155
	global_store_dwordx4 v132, v[156:159], s[24:25] nt
	ds_read2_b32 v[148:149], v129 offset0:56 offset1:121
	ds_read2_b32 v[150:151], v129 offset0:186 offset1:251
	ds_read2_b32 v[152:153], v130 offset0:60 offset1:125
	ds_read2_b32 v[154:155], v130 offset0:190 offset1:255
	s_add_u32 s24, s22, 0x103800
	s_addc_u32 s25, s23, 0
	s_waitcnt lgkmcnt(4)
	v_cvt_pk_bf16_f32 v142, v134, v135
	v_cvt_pk_bf16_f32 v143, v136, v137
	v_cvt_pk_bf16_f32 v144, v138, v139
	v_cvt_pk_bf16_f32 v145, v140, v141
	global_store_dwordx4 v132, v[142:145], s[24:25] nt
	s_add_u32 s24, s22, 0x12ec00
	s_addc_u32 s25, s23, 0
	s_waitcnt lgkmcnt(0)
	v_cvt_pk_bf16_f32 v156, v148, v149
	v_cvt_pk_bf16_f32 v157, v150, v151
	v_cvt_pk_bf16_f32 v158, v152, v153
	v_cvt_pk_bf16_f32 v159, v154, v155
	global_store_dwordx4 v132, v[156:159], s[24:25] nt
	s_add_u32 s22, s22, 0x400
	s_addc_u32 s23, s23, 0
	s_add_i32 s26, s26, 1
	s_cmp_ge_u32 s26, 14
	s_cbranch_scc1 .Lhn_fin
	s_cmp_eq_u32 s26, 1
	s_cbranch_scc0 .Lhn_w1
	s_waitcnt vmcnt(24)
.Lhn_w1:
	s_waitcnt vmcnt(32)
	ds_write2_b32 v128, v64, v65 offset1:1
	ds_write2_b32 v128, v66, v67 offset0:2 offset1:3
	v_add_u32_e32 v133, 0x410, v128
	ds_write2_b32 v133, v68, v69 offset1:1
	ds_write2_b32 v133, v70, v71 offset0:2 offset1:3
	v_add_u32_e32 v147, 0x820, v128
	ds_write2_b32 v147, v72, v73 offset1:1
	ds_write2_b32 v147, v74, v75 offset0:2 offset1:3
	v_add_u32_e32 v133, 0xc30, v128
	ds_write2_b32 v133, v76, v77 offset1:1
	ds_write2_b32 v133, v78, v79 offset0:2 offset1:3
	v_add_u32_e32 v147, 0x1040, v128
	ds_write2_b32 v147, v80, v81 offset1:1
	ds_write2_b32 v147, v82, v83 offset0:2 offset1:3
	v_add_u32_e32 v133, 0x1450, v128
	ds_write2_b32 v133, v84, v85 offset1:1
	ds_write2_b32 v133, v86, v87 offset0:2 offset1:3
	v_add_u32_e32 v147, 0x1860, v128
	ds_write2_b32 v147, v88, v89 offset1:1
	ds_write2_b32 v147, v90, v91 offset0:2 offset1:3
	v_add_u32_e32 v133, 0x1c70, v128
	ds_write2_b32 v133, v92, v93 offset1:1
	ds_write2_b32 v133, v94, v95 offset0:2 offset1:3
	v_add_u32_e32 v147, 0x2080, v128
	ds_write2_b32 v147, v96, v97 offset1:1
	ds_write2_b32 v147, v98, v99 offset0:2 offset1:3
	v_add_u32_e32 v133, 0x2490, v128
	ds_write2_b32 v133, v100, v101 offset1:1
	ds_write2_b32 v133, v102, v103 offset0:2 offset1:3
	v_add_u32_e32 v147, 0x28a0, v128
	ds_write2_b32 v147, v104, v105 offset1:1
	ds_write2_b32 v147, v106, v107 offset0:2 offset1:3
	v_add_u32_e32 v133, 0x2cb0, v128
	ds_write2_b32 v133, v108, v109 offset1:1
	ds_write2_b32 v133, v110, v111 offset0:2 offset1:3
	v_add_u32_e32 v147, 0x30c0, v128
	ds_write2_b32 v147, v112, v113 offset1:1
	ds_write2_b32 v147, v114, v115 offset0:2 offset1:3
	v_add_u32_e32 v133, 0x34d0, v128
	ds_write2_b32 v133, v116, v117 offset1:1
	ds_write2_b32 v133, v118, v119 offset0:2 offset1:3
	v_add_u32_e32 v147, 0x38e0, v128
	ds_write2_b32 v147, v120, v121 offset1:1
	ds_write2_b32 v147, v122, v123 offset0:2 offset1:3
	v_add_u32_e32 v133, 0x3cf0, v128
	ds_write2_b32 v133, v124, v125 offset1:1
	ds_write2_b32 v133, v126, v127 offset0:2 offset1:3
	s_waitcnt lgkmcnt(0)
; #define LAS __attribute__((address_space(3)))
; __device__ __forceinline__ unsigned pk2(float lo, float hi) { return pg8::cvt_pk_bf16(lo, hi); }
; __device__ __forceinline__ void p0_load(const float* W, int N, int k0, int n0, int lane, f32x4 (&v)[16]) {
;     const int c = lane & 15, rq = lane >> 4;
;     int col = n0 + 4 * c; col = col < N - 4 ? col : N - 4;
;     const float* p = W + (size_t)(k0 + rq) * N + col;
; #pragma unroll
;     for (int j = 0; j < 16; ++j) v[j] = __builtin_nontemporal_load((const f32x4*)(p + (size_t)(4 * j) * N));
; }
; __device__ __forceinline__ void p0_finish(bf16* WT, const float* gain, int N, int k0, int n0, int ldw, int blk, int off, int lane, const f32x4 (&v)[16], LAS float* scr) {
;     const int c = lane & 15, rq = lane >> 4, c8 = lane & 7;
;     f32x4 g0 = {1.f, 1.f, 1.f, 1.f}, g1 = g0;
;     if (gain) { g0 = *(const f32x4*)(gain + k0 + 8 * c8); g1 = *(const f32x4*)(gain + k0 + 8 * c8 + 4); }
; #pragma unroll
;     for (int j = 0; j < 16; ++j) { LAS float* s = scr + (4 * j + rq) * 65 + 4 * c; s[0] = v[j][0]; s[1] = v[j][1]; s[2] = v[j][2]; s[3] = v[j][3]; }
;     asm volatile("s_waitcnt lgkmcnt(0)" ::: "memory");
; #pragma unroll
;     for (int jj = 0; jj < 8; ++jj) { const int n = (lane >> 3) + 8 * jj; const LAS float* s = scr + (8 * c8) * 65 + n;
;         u32x4 o; o.x = pk2(s[0 * 65] * g0[0], s[1 * 65] * g0[1]); o.y = pk2(s[2 * 65] * g0[2], s[3 * 65] * g0[3]); o.z = pk2(s[4 * 65] * g1[0], s[5 * 65] * g1[1]); o.w = pk2(s[6 * 65] * g1[2], s[7 * 65] * g1[3]);
;         const int ng = n0 + n;
;         if (ng < N) { const int row = (ng >> 7) * blk + (ng & 127) + off; __builtin_nontemporal_store(o, (u32x4*)(WT + (size_t)row * ldw + k0 + 8 * c8)); } }
;     asm volatile("s_waitcnt lgkmcnt(0)" ::: "memory");
; }
	s_cmp_lt_u32 s27, 14
	s_cselect_b32 s2, 0x800000, 0
	s_add_u32 s20, s20, s2
	s_addc_u32 s21, s21, 0
	s_add_i32 s27, s27, 1
	global_load_dwordx4 v[64:67], v131, s[20:21] nt
	s_add_u32 s24, s20, 0x10000
	s_addc_u32 s25, s21, 0
	global_load_dwordx4 v[68:71], v131, s[24:25] nt
	s_add_u32 s24, s20, 0x20000
	s_addc_u32 s25, s21, 0
	global_load_dwordx4 v[72:75], v131, s[24:25] nt
	s_add_u32 s24, s20, 0x30000
	s_addc_u32 s25, s21, 0
	global_load_dwordx4 v[76:79], v131, s[24:25] nt
	s_add_u32 s24, s20, 0x40000
	s_addc_u32 s25, s21, 0
	global_load_dwordx4 v[80:83], v131, s[24:25] nt
	s_add_u32 s24, s20, 0x50000
	s_addc_u32 s25, s21, 0
	global_load_dwordx4 v[84:87], v131, s[24:25] nt
	s_add_u32 s24, s20, 0x60000
	s_addc_u32 s25, s21, 0
	global_load_dwordx4 v[88:91], v131, s[24:25] nt
	s_add_u32 s24, s20, 0x70000
	s_addc_u32 s25, s21, 0
	global_load_dwordx4 v[92:95], v131, s[24:25] nt
	s_add_u32 s24, s20, 0x80000
	s_addc_u32 s25, s21, 0
	global_load_dwordx4 v[96:99], v131, s[24:25] nt
	s_add_u32 s24, s20, 0x90000
	s_addc_u32 s25, s21, 0
	global_load_dwordx4 v[100:103], v131, s[24:25] nt
	s_add_u32 s24, s20, 0xa0000
	s_addc_u32 s25, s21, 0
	global_load_dwordx4 v[104:107], v131, s[24:25] nt
	s_add_u32 s24, s20, 0xb0000
	s_addc_u32 s25, s21, 0
	global_load_dwordx4 v[108:111], v131, s[24:25] nt
	s_add_u32 s24, s20, 0xc0000
	s_addc_u32 s25, s21, 0
	global_load_dwordx4 v[112:115], v131, s[24:25] nt
	s_add_u32 s24, s20, 0xd0000
	s_addc_u32 s25, s21, 0
	global_load_dwordx4 v[116:119], v131, s[24:25] nt
	s_add_u32 s24, s20, 0xe0000
	s_addc_u32 s25, s21, 0
	global_load_dwordx4 v[120:123], v131, s[24:25] nt
	s_add_u32 s24, s20, 0xf0000
	s_addc_u32 s25, s21, 0
	global_load_dwordx4 v[124:127], v131, s[24:25] nt
	ds_read2_b32 v[134:135], v129 offset0:0 offset1:65
	ds_read2_b32 v[136:137], v129 offset0:130 offset1:195
	ds_read2_b32 v[138:139], v130 offset0:4 offset1:69
	ds_read2_b32 v[140:141], v130 offset0:134 offset1:199
	ds_read2_b32 v[148:149], v129 offset0:8 offset1:73
	ds_read2_b32 v[150:151], v129 offset0:138 offset1:203
	ds_read2_b32 v[152:153], v130 offset0:12 offset1:77
	ds_read2_b32 v[154:155], v130 offset0:142 offset1:207
	s_mov_b64 s[24:25], s[22:23]
	s_waitcnt lgkmcnt(4)
	v_cvt_pk_bf16_f32 v142, v134, v135
	v_cvt_pk_bf16_f32 v143, v136, v137
	v_cvt_pk_bf16_f32 v144, v138, v139
	v_cvt_pk_bf16_f32 v145, v140, v141
	global_store_dwordx4 v132, v[142:145], s[24:25] nt
	ds_read2_b32 v[134:135], v129 offset0:16 offset1:81
	ds_read2_b32 v[136:137], v129 offset0:146 offset1:211
	ds_read2_b32 v[138:139], v130 offset0:20 offset1:85
	ds_read2_b32 v[140:141], v130 offset0:150 offset1:215
	s_add_u32 s24, s22, 0x2b400
	s_addc_u32 s25, s23, 0
	s_waitcnt lgkmcnt(4)
	v_cvt_pk_bf16_f32 v156, v148, v149
	v_cvt_pk_bf16_f32 v157, v150, v151
	v_cvt_pk_bf16_f32 v158, v152, v153
	v_cvt_pk_bf16_f32 v159, v154, v155
	global_store_dwordx4 v132, v[156:159], s[24:25] nt
	ds_read2_b32 v[148:149], v129 offset0:24 offset1:89
	ds_read2_b32 v[150:151], v129 offset0:154 offset1:219
	ds_read2_b32 v[152:153], v130 offset0:28 offset1:93
	ds_read2_b32 v[154:155], v130 offset0:158 offset1:223
	s_add_u32 s24, s22, 0x56800
	s_addc_u32 s25, s23, 0
	s_waitcnt lgkmcnt(4)
	v_cvt_pk_bf16_f32 v142, v134, v135
	v_cvt_pk_bf16_f32 v143, v136, v137
	v_cvt_pk_bf16_f32 v144, v138, v139
	v_cvt_pk_bf16_f32 v145, v140, v141
	global_store_dwordx4 v132, v[142:145], s[24:25] nt
	ds_read2_b32 v[134:135], v129 offset0:32 offset1:97
	ds_read2_b32 v[136:137], v129 offset0:162 offset1:227
	ds_read2_b32 v[138:139], v130 offset0:36 offset1:101
	ds_read2_b32 v[140:141], v130 offset0:166 offset1:231
	s_add_u32 s24, s22, 0x81c00
	s_addc_u32 s25, s23, 0
	s_waitcnt lgkmcnt(4)
	v_cvt_pk_bf16_f32 v156, v148, v149
	v_cvt_pk_bf16_f32 v157, v150, v151
	v_cvt_pk_bf16_f32 v158, v152, v153
	v_cvt_pk_bf16_f32 v159, v154, v155
	global_store_dwordx4 v132, v[156:159], s[24:25] nt
	ds_read2_b32 v[148:149], v129 offset0:40 offset1:105
	ds_read2_b32 v[150:151], v129 offset0:170 offset1:235
	ds_read2_b32 v[152:153], v130 offset0:44 offset1:109
	ds_read2_b32 v[154:155], v130 offset0:174 offset1:239
	s_add_u32 s24, s22, 0xad000
	s_addc_u32 s25, s23, 0
	s_waitcnt lgkmcnt(4)
	v_cvt_pk_bf16_f32 v142, v134, v135
	v_cvt_pk_bf16_f32 v143, v136, v137
	v_cvt_pk_bf16_f32 v144, v138, v139
	v_cvt_pk_bf16_f32 v145, v140, v141
	global_store_dwordx4 v132, v[142:145], s[24:25] nt
	ds_read2_b32 v[134:135], v129 offset0:48 offset1:113
	ds_read2_b32 v[136:137], v129 offset0:178 offset1:243
	ds_read2_b32 v[138:139], v130 offset0:52 offset1:117
	ds_read2_b32 v[140:141], v130 offset0:182 offset1:247
	s_add_u32 s24, s22, 0xd8400
	s_addc_u32 s25, s23, 0
	s_waitcnt lgkmcnt(4)
	v_cvt_pk_bf16_f32 v156, v148, v149
	v_cvt_pk_bf16_f32 v157, v150, v151
	v_cvt_pk_bf16_f32 v158, v152, v153
	v_cvt_pk_bf16_f32 v159, v154, v155
	global_store_dwordx4 v132, v[156:159], s[24:25] nt
	ds_read2_b32 v[148:149], v129 offset0:56 offset1:121
	ds_read2_b32 v[150:151], v129 offset0:186 offset1:251
	ds_read2_b32 v[152:153], v130 offset0:60 offset1:125
	ds_read2_b32 v[154:155], v130 offset0:190 offset1:255
	s_add_u32 s24, s22, 0x103800
	s_addc_u32 s25, s23, 0
	s_waitcnt lgkmcnt(4)
	v_cvt_pk_bf16_f32 v142, v134, v135
	v_cvt_pk_bf16_f32 v143, v136, v137
	v_cvt_pk_bf16_f32 v144, v138, v139
	v_cvt_pk_bf16_f32 v145, v140, v141
	global_store_dwordx4 v132, v[142:145], s[24:25] nt
	s_add_u32 s24, s22, 0x12ec00
	s_addc_u32 s25, s23, 0
	s_waitcnt lgkmcnt(0)
	v_cvt_pk_bf16_f32 v156, v148, v149
	v_cvt_pk_bf16_f32 v157, v150, v151
	v_cvt_pk_bf16_f32 v158, v152, v153
	v_cvt_pk_bf16_f32 v159, v154, v155
	global_store_dwordx4 v132, v[156:159], s[24:25] nt
	s_add_u32 s22, s22, 0x400
	s_addc_u32 s23, s23, 0
	s_add_i32 s26, s26, 1
	s_cmp_lt_u32 s26, 14
	s_cbranch_scc1 .Lhn_loop
